# w_out copy (transpose_items<3>, P0 and P2 tail): the group-gain vector was loaded four times per item with a full wait each time; loaded once and copied (2 wait states kept behind each 128-bit store b
# baseline (speedup 1.0000x reference)
.LBB0_89:
	s_lshr_b32 s2, s4, 1
	s_and_b32 s2, s2, 0x7fffffc0
	s_sub_i32 s26, 0, s2
	s_waitcnt lgkmcnt(0)
	s_ashr_i32 s27, s26, 31
	v_lshl_add_u64 v[54:55], s[26:27], 2, v[40:41]
	global_load_dwordx4 v[46:49], v[54:55], off
	global_load_dwordx4 v[50:53], v[54:55], off offset:16
	ds_read2_b32 v[58:59], v42 offset0:33 offset1:41
	ds_read2_b32 v[60:61], v42 offset1:8
	ds_read2_b32 v[62:63], v42 offset0:66 offset1:74
	ds_read2_b32 v[64:65], v42 offset0:99 offset1:107
	ds_read2_b32 v[66:67], v42 offset0:132 offset1:140
	ds_read2_b32 v[68:69], v42 offset0:165 offset1:173
	ds_read2_b32 v[70:71], v42 offset0:198 offset1:206
	ds_read2_b32 v[72:73], v42 offset0:231 offset1:239
	s_and_b32 s2, s25, 0xfe0
	v_subrev_u32_e32 v56, s2, v1
	v_ashrrev_i32_e32 v57, 31, v56
	s_waitcnt lgkmcnt(6)
	v_mov_b32_e32 v76, v60
	v_mov_b32_e32 v77, v58
	s_waitcnt lgkmcnt(5)
	v_mov_b32_e32 v78, v62
	s_waitcnt lgkmcnt(4)
	v_mov_b32_e32 v79, v64
	s_waitcnt lgkmcnt(3)
	v_mov_b32_e32 v80, v66
	s_waitcnt lgkmcnt(2)
	v_mov_b32_e32 v81, v68
	s_waitcnt lgkmcnt(1)
	v_mov_b32_e32 v82, v70
	s_waitcnt lgkmcnt(0)
	v_mov_b32_e32 v83, v72
	v_lshlrev_b64 v[56:57], 13, v[56:57]
	v_lshl_add_u64 v[74:75], s[26:27], 1, v[36:37]
	v_lshl_add_u64 v[56:57], v[74:75], 0, v[56:57]
	v_mov_b32_e32 v58, v61
	v_mov_b32_e32 v64, v63
	v_mov_b32_e32 v68, v67
	v_mov_b32_e32 v72, v71
	s_sub_i32 s4, s4, s56
	s_and_b64 vcc, exec, s[0:1]
	s_mov_b32 s25, s24
	s_waitcnt vmcnt(1)
	v_mov_b64_e32 v[200:201], v[46:47]
	v_mov_b64_e32 v[202:203], v[48:49]
	v_pk_mul_f32 v[46:47], v[46:47], v[76:77]
	v_pk_mul_f32 v[48:49], v[48:49], v[78:79]
	s_waitcnt vmcnt(0)
	v_mov_b64_e32 v[204:205], v[50:51]
	v_mov_b64_e32 v[206:207], v[52:53]
	v_pk_mul_f32 v[50:51], v[50:51], v[80:81]
	v_pk_mul_f32 v[52:53], v[52:53], v[82:83]
	v_cvt_pk_bf16_f32 v46, v46, v47
	v_cvt_pk_bf16_f32 v47, v48, v49
	v_cvt_pk_bf16_f32 v48, v50, v51
	v_cvt_pk_bf16_f32 v49, v52, v53
	global_store_dwordx4 v[56:57], v[46:49], off nt
	s_nop 1
	v_mov_b64_e32 v[46:47], v[200:201]
	v_mov_b64_e32 v[48:49], v[202:203]
	s_nop 0
	v_mov_b64_e32 v[50:51], v[204:205]
	v_mov_b64_e32 v[52:53], v[206:207]
	v_subrev_u32_e32 v56, s2, v43
	v_ashrrev_i32_e32 v57, 31, v56
	v_lshlrev_b64 v[56:57], 13, v[56:57]
	v_lshl_add_u64 v[56:57], v[74:75], 0, v[56:57]
	v_pk_mul_f32 v[46:47], v[46:47], v[58:59]
	v_pk_mul_f32 v[48:49], v[48:49], v[64:65]
	v_pk_mul_f32 v[50:51], v[50:51], v[68:69]
	v_pk_mul_f32 v[52:53], v[52:53], v[72:73]
	v_cvt_pk_bf16_f32 v46, v46, v47
	v_cvt_pk_bf16_f32 v47, v48, v49
	v_cvt_pk_bf16_f32 v48, v50, v51
	v_cvt_pk_bf16_f32 v49, v52, v53
	global_store_dwordx4 v[56:57], v[46:49], off nt
	s_nop 1
	v_mov_b64_e32 v[46:47], v[200:201]
	v_mov_b64_e32 v[48:49], v[202:203]
	s_nop 0
	v_mov_b64_e32 v[50:51], v[204:205]
	v_mov_b64_e32 v[52:53], v[206:207]
	ds_read2_b32 v[58:59], v42 offset0:16 offset1:24
	ds_read2_b32 v[60:61], v42 offset0:49 offset1:57
	ds_read2_b32 v[62:63], v42 offset0:82 offset1:90
	ds_read2_b32 v[64:65], v42 offset0:115 offset1:123
	ds_read2_b32 v[66:67], v42 offset0:148 offset1:156
	ds_read2_b32 v[68:69], v42 offset0:181 offset1:189
	ds_read2_b32 v[70:71], v42 offset0:214 offset1:222
	ds_read2_b32 v[72:73], v42 offset0:247 offset1:255
	v_subrev_u32_e32 v56, s2, v44
	v_ashrrev_i32_e32 v57, 31, v56
	s_waitcnt lgkmcnt(7)
	v_mov_b32_e32 v76, v58
	s_waitcnt lgkmcnt(6)
	v_mov_b32_e32 v77, v60
	s_waitcnt lgkmcnt(5)
	v_mov_b32_e32 v78, v62
	s_waitcnt lgkmcnt(4)
	v_mov_b32_e32 v79, v64
	s_waitcnt lgkmcnt(3)
	v_mov_b32_e32 v80, v66
	s_waitcnt lgkmcnt(2)
	v_mov_b32_e32 v81, v68
	s_waitcnt lgkmcnt(1)
	v_mov_b32_e32 v82, v70
	s_waitcnt lgkmcnt(0)
	v_mov_b32_e32 v83, v72
	v_lshlrev_b64 v[56:57], 13, v[56:57]
	v_lshl_add_u64 v[56:57], v[74:75], 0, v[56:57]
	v_mov_b32_e32 v60, v59
	v_mov_b32_e32 v64, v63
	v_mov_b32_e32 v68, v67
	v_mov_b32_e32 v72, v71
	v_pk_mul_f32 v[46:47], v[46:47], v[76:77]
	v_pk_mul_f32 v[48:49], v[48:49], v[78:79]
	v_pk_mul_f32 v[50:51], v[50:51], v[80:81]
	v_pk_mul_f32 v[52:53], v[52:53], v[82:83]
	v_cvt_pk_bf16_f32 v46, v46, v47
	v_cvt_pk_bf16_f32 v47, v48, v49
	v_cvt_pk_bf16_f32 v48, v50, v51
	v_cvt_pk_bf16_f32 v49, v52, v53
	global_store_dwordx4 v[56:57], v[46:49], off nt
	s_nop 1
	v_mov_b64_e32 v[46:47], v[200:201]
	v_mov_b64_e32 v[48:49], v[202:203]
	s_nop 0
	v_mov_b64_e32 v[50:51], v[204:205]
	v_mov_b64_e32 v[52:53], v[206:207]
	v_subrev_u32_e32 v54, s2, v45
	v_ashrrev_i32_e32 v55, 31, v54
	v_lshlrev_b64 v[54:55], 13, v[54:55]
	v_lshl_add_u64 v[54:55], v[74:75], 0, v[54:55]
	v_pk_mul_f32 v[46:47], v[46:47], v[60:61]
	v_pk_mul_f32 v[48:49], v[48:49], v[64:65]
	v_pk_mul_f32 v[50:51], v[50:51], v[68:69]
	v_pk_mul_f32 v[52:53], v[52:53], v[72:73]
	v_cvt_pk_bf16_f32 v46, v46, v47
	v_cvt_pk_bf16_f32 v47, v48, v49
	v_cvt_pk_bf16_f32 v48, v50, v51
	v_cvt_pk_bf16_f32 v49, v52, v53
	global_store_dwordx4 v[54:55], v[46:49], off nt
	s_waitcnt lgkmcnt(0)
	s_cbranch_vccnz .LBB0_77

.LBB0_394:
	s_ashr_i32 s13, s11, 31
	s_lshr_b32 s13, s13, 25
	s_add_i32 s11, s11, s13
	s_ashr_i32 s11, s11, 7
	s_lshl_b32 s18, s11, 6
	s_waitcnt lgkmcnt(0)
	s_ashr_i32 s19, s18, 31
	v_lshl_add_u64 v[54:55], s[18:19], 2, v[42:43]
	global_load_dwordx4 v[46:49], v[54:55], off
	global_load_dwordx4 v[50:53], v[54:55], off offset:16
	ds_read2_b32 v[60:61], v35 offset0:33 offset1:41
	ds_read2_b32 v[62:63], v35 offset1:8
	ds_read2_b32 v[64:65], v35 offset0:66 offset1:74
	ds_read2_b32 v[66:67], v35 offset0:99 offset1:107
	ds_read2_b32 v[68:69], v35 offset0:132 offset1:140
	ds_read2_b32 v[70:71], v35 offset0:165 offset1:173
	ds_read2_b32 v[72:73], v35 offset0:198 offset1:206
	ds_read2_b32 v[74:75], v35 offset0:231 offset1:239
	v_add_u32_e32 v37, s9, v1
	s_lshl_b32 s11, s11, 12
	v_subrev_u32_e32 v37, s11, v37
	v_add_u32_e32 v78, 0xffff4000, v37
	s_waitcnt lgkmcnt(6)
	v_mov_b32_e32 v80, v62
	v_mov_b32_e32 v81, v60
	s_waitcnt lgkmcnt(5)
	v_mov_b32_e32 v82, v64
	s_waitcnt lgkmcnt(4)
	v_mov_b32_e32 v83, v66
	s_waitcnt lgkmcnt(3)
	v_mov_b32_e32 v84, v68
	s_waitcnt lgkmcnt(2)
	v_mov_b32_e32 v85, v70
	s_waitcnt lgkmcnt(1)
	v_mov_b32_e32 v86, v72
	s_waitcnt lgkmcnt(0)
	v_mov_b32_e32 v87, v74
	v_ashrrev_i32_e32 v79, 31, v78
	v_lshl_add_u64 v[76:77], s[18:19], 1, v[44:45]
	v_lshlrev_b64 v[78:79], 13, v[78:79]
	v_lshl_add_u64 v[78:79], v[76:77], 0, v[78:79]
	v_add_u32_e32 v62, 0xffff4008, v37
	v_mov_b32_e32 v60, v63
	v_mov_b32_e32 v66, v65
	v_mov_b32_e32 v70, v69
	v_mov_b32_e32 v74, v73
	v_ashrrev_i32_e32 v63, 31, v62
	v_lshlrev_b64 v[62:63], 13, v[62:63]
	v_lshl_add_u64 v[62:63], v[76:77], 0, v[62:63]
	s_add_i32 s9, s9, 0xc000
	s_andn2_b64 vcc, exec, s[0:1]
	s_mov_b32 s11, s10
	s_waitcnt vmcnt(1)
	v_mov_b64_e32 v[200:201], v[46:47]
	v_mov_b64_e32 v[202:203], v[48:49]
	v_pk_mul_f32 v[46:47], v[46:47], v[80:81]
	v_pk_mul_f32 v[48:49], v[48:49], v[82:83]
	s_waitcnt vmcnt(0)
	v_mov_b64_e32 v[204:205], v[50:51]
	v_mov_b64_e32 v[206:207], v[52:53]
	v_pk_mul_f32 v[50:51], v[50:51], v[84:85]
	v_pk_mul_f32 v[52:53], v[52:53], v[86:87]
	v_cvt_pk_bf16_f32 v46, v46, v47
	v_cvt_pk_bf16_f32 v47, v48, v49
	v_cvt_pk_bf16_f32 v48, v50, v51
	v_cvt_pk_bf16_f32 v49, v52, v53
	global_store_dwordx4 v[78:79], v[46:49], off nt
	s_nop 1
	v_mov_b64_e32 v[46:47], v[200:201]
	v_mov_b64_e32 v[48:49], v[202:203]
	s_nop 0
	v_mov_b64_e32 v[50:51], v[204:205]
	v_mov_b64_e32 v[52:53], v[206:207]
	v_add_u32_e32 v78, 0xffff4010, v37
	v_ashrrev_i32_e32 v79, 31, v78
	v_lshlrev_b64 v[78:79], 13, v[78:79]
	v_lshl_add_u64 v[78:79], v[76:77], 0, v[78:79]
	v_pk_mul_f32 v[46:47], v[46:47], v[60:61]
	v_pk_mul_f32 v[48:49], v[48:49], v[66:67]
	v_pk_mul_f32 v[50:51], v[50:51], v[70:71]
	v_pk_mul_f32 v[52:53], v[52:53], v[74:75]
	v_cvt_pk_bf16_f32 v46, v46, v47
	v_cvt_pk_bf16_f32 v47, v48, v49
	v_cvt_pk_bf16_f32 v48, v50, v51
	v_cvt_pk_bf16_f32 v49, v52, v53
	global_store_dwordx4 v[62:63], v[46:49], off nt
	s_nop 1
	v_mov_b64_e32 v[46:47], v[200:201]
	v_mov_b64_e32 v[48:49], v[202:203]
	s_nop 0
	v_mov_b64_e32 v[50:51], v[204:205]
	v_mov_b64_e32 v[52:53], v[206:207]
	ds_read2_b32 v[60:61], v35 offset0:16 offset1:24
	ds_read2_b32 v[62:63], v35 offset0:49 offset1:57
	ds_read2_b32 v[64:65], v35 offset0:82 offset1:90
	ds_read2_b32 v[66:67], v35 offset0:115 offset1:123
	ds_read2_b32 v[68:69], v35 offset0:148 offset1:156
	ds_read2_b32 v[70:71], v35 offset0:181 offset1:189
	ds_read2_b32 v[72:73], v35 offset0:214 offset1:222
	ds_read2_b32 v[74:75], v35 offset0:247 offset1:255
	s_waitcnt lgkmcnt(7)
	v_mov_b32_e32 v80, v60
	s_waitcnt lgkmcnt(6)
	v_mov_b32_e32 v81, v62
	s_waitcnt lgkmcnt(5)
	v_mov_b32_e32 v82, v64
	s_waitcnt lgkmcnt(4)
	v_mov_b32_e32 v83, v66
	s_waitcnt lgkmcnt(3)
	v_mov_b32_e32 v84, v68
	s_waitcnt lgkmcnt(2)
	v_mov_b32_e32 v85, v70
	s_waitcnt lgkmcnt(1)
	v_mov_b32_e32 v86, v72
	s_waitcnt lgkmcnt(0)
	v_mov_b32_e32 v87, v74
	v_mov_b32_e32 v62, v61
	v_mov_b32_e32 v66, v65
	v_mov_b32_e32 v70, v69
	v_mov_b32_e32 v74, v73
	v_pk_mul_f32 v[46:47], v[46:47], v[80:81]
	v_pk_mul_f32 v[48:49], v[48:49], v[82:83]
	v_pk_mul_f32 v[50:51], v[50:51], v[84:85]
	v_pk_mul_f32 v[52:53], v[52:53], v[86:87]
	v_cvt_pk_bf16_f32 v46, v46, v47
	v_cvt_pk_bf16_f32 v47, v48, v49
	v_cvt_pk_bf16_f32 v48, v50, v51
	v_cvt_pk_bf16_f32 v49, v52, v53
	global_store_dwordx4 v[78:79], v[46:49], off nt
	s_nop 1
	v_mov_b64_e32 v[46:47], v[200:201]
	v_mov_b64_e32 v[48:49], v[202:203]
	s_nop 0
	v_mov_b64_e32 v[50:51], v[204:205]
	v_mov_b64_e32 v[52:53], v[206:207]
	v_add_u32_e32 v54, 0xffff4018, v37
	v_ashrrev_i32_e32 v55, 31, v54
	v_lshlrev_b64 v[54:55], 13, v[54:55]
	v_lshl_add_u64 v[54:55], v[76:77], 0, v[54:55]
	v_pk_mul_f32 v[46:47], v[46:47], v[62:63]
	v_pk_mul_f32 v[48:49], v[48:49], v[66:67]
	v_pk_mul_f32 v[50:51], v[50:51], v[70:71]
	v_pk_mul_f32 v[52:53], v[52:53], v[74:75]
	v_cvt_pk_bf16_f32 v46, v46, v47
	v_cvt_pk_bf16_f32 v47, v48, v49
	v_cvt_pk_bf16_f32 v48, v50, v51
	v_cvt_pk_bf16_f32 v49, v52, v53
	global_store_dwordx4 v[54:55], v[46:49], off nt
	s_waitcnt lgkmcnt(0)
	s_cbranch_vccz .LBB0_397
